# adaLN-RMSNorm latent loops (both instances) rewritten: gain hoisted, modulation vectors fetched once per iteration, next rows prefetched during the store phase
# speedup vs baseline: 1.0137x; 1.0017x over previous
; DI void normmod_phase(const float* xl, const float* xc, const float* g, const float* modl  , int cshift, int cscale, bf16_t* H, int nrows, int gw, int NGW, int lane,
;                       const float* part  , const float* pgate  , float* xc_out) {
;     auto ld = [&](const int row, f32x4 (&v)[4]) __attribute__((always_inline)) -> float {
;         const bool lat = row < ML;
;         const float* xr = lat ? xl + (size_t)row * D : xc + (size_t)(row - ML) * D;
;         float ss = 0.f;
; #pragma unroll
;         for (int j = 0; j < 4; ++j) { v[j] = *(const f32x4*)(xr + lane * 4 + 256 * j);
;             if (part && !lat) {
;                 const size_t po = (size_t)(row - ML) * D + lane * 4 + 256 * j;
;                 const f32x4 p0 = *(const f32x4*)(part + po), p1 = *(const f32x4*)(part + (size_t)MC * D + po), p2 = *(const f32x4*)(part + (size_t)2 * MC * D + po), p3 = *(const f32x4*)(part + (size_t)3 * MC * D + po);
;                 v[j] = v[j] + *(const f32x4*)(pgate + lane * 4 + 256 * j) * ((p0 + p1) + (p2 + p3));
;                 *(f32x4*)(xc_out + po) = v[j]; }
;             ss += (v[j][0] * v[j][0] + v[j][1] * v[j][1]) + (v[j][2] * v[j][2] + v[j][3] * v[j][3]); }
;         return ss; };
;     auto st = [&](const int row, const f32x4 (&v)[4], const float rs) __attribute__((always_inline)) {
;         const float* mp = modl + (size_t)((row < ML) ? (row >> 12) : 16) * 6144;
; #pragma unroll
;         for (int j = 0; j < 4; ++j) { const int c = lane * 4 + 256 * j;
;             const f32x4 gg = *(const f32x4*)(g + c), sh = *(const f32x4*)(mp + cshift * 1024 + c), scl = *(const f32x4*)(mp + cscale * 1024 + c);
;             const f32x4 y = (v[j] * rs) * gg * (scl + 1.f) + sh;
;             u32x2 o; o.x = pk2(y[0], y[1]); o.y = pk2(y[2], y[3]);
;             *(u32x2*)(H + (size_t)row * D + c) = o; } };
;     for (int row = gw * 4; row < (nrows < ML ? nrows : ML); row += NGW * 4) {
;         f32x4 vA[4], vB[4], vC[4], vD[4];
;         float sA = ld(row, vA), sB = ld(row + 1, vB), sC = ld(row + 2, vC), sD = ld(row + 3, vD);
; #pragma unroll
;         for (int o = 1; o < 64; o <<= 1) { sA += __shfl_xor(sA, o); sB += __shfl_xor(sB, o); sC += __shfl_xor(sC, o); sD += __shfl_xor(sD, o); }
;         st(row, vA, rsqrtf(sA * (1.f / D) + EPS)); st(row + 1, vB, rsqrtf(sB * (1.f / D) + EPS));
.LBB0_314:
	s_lshl_b32 s8, s69, 12
	s_add_u32 s4, s4, s8
	s_addc_u32 s5, s5, 0
	s_add_u32 s8, s84, 0x312dc000
	v_readlane_b32 s56, v253, 23
	s_addc_u32 s9, s85, 0
	v_readlane_b32 s57, v253, 24
	s_and_b64 s[26:27], s[56:57], exec
	s_cselect_b32 s25, 0, s8
	s_cselect_b32 s20, 0, s9
	s_add_u32 s38, s25, 0x1000000
	s_addc_u32 s39, s20, 0
	s_add_u32 s40, s25, 0x2000000
	s_addc_u32 s41, s20, 0
	s_add_u32 s42, s25, 0x3000000
	v_lshlrev_b32_e32 v69, 2, v152
	v_lshlrev_b32_e32 v74, 4, v152
	v_mov_b32_e32 v75, v149
	s_addc_u32 s43, s20, 0
	v_lshl_add_u64 v[0:1], s[16:17], 0, v[74:75]
	s_mov_b64 s[26:27], 0x62000
	v_or_b32_e32 v68, 0x100, v69
	v_or_b32_e32 v70, 0x200, v69
	v_or_b32_e32 v72, 0x300, v69
	s_cmpk_gt_i32 s36, 0x3fff
	v_lshl_add_u64 v[64:65], v[0:1], 0, s[26:27]
	v_lshl_add_u64 v[66:67], s[4:5], 0, v[74:75]
	v_lshlrev_b32_e32 v71, 2, v68
	v_lshlrev_b32_e32 v73, 2, v70
	v_lshlrev_b32_e32 v80, 2, v72
	s_cbranch_scc1 .LBB0_353
	v_xor_b32_e32 v0, 1, v210
	v_cmp_lt_i32_e32 vcc, v0, v250
	s_lshl_b32 s5, s96, 5
	s_lshl_b32 s20, s37, 2
	v_cndmask_b32_e32 v0, v210, v0, vcc
	v_lshlrev_b32_e32 v81, 2, v0
	v_xor_b32_e32 v0, 2, v210
	v_cmp_lt_i32_e32 vcc, v0, v250
	s_lshl_b32 s4, s36, 2
	s_add_i32 s5, s5, s20
	v_cndmask_b32_e32 v0, v210, v0, vcc
	v_cmp_lt_i32_e32 vcc, v251, v250
	v_lshlrev_b32_e32 v82, 2, v0
	s_add_i32 s20, s5, 0xffff0001
	v_cndmask_b32_e32 v0, v210, v251, vcc
	v_lshlrev_b32_e32 v83, 2, v0
	v_xor_b32_e32 v0, 8, v210
	s_ashr_i32 s5, s4, 31
	s_lshl_b32 s26, s33, 5
	v_cmp_lt_i32_e32 vcc, v0, v250
	s_lshl_b64 s[30:31], s[4:5], 12
	s_add_u32 s44, s10, s30
	v_cndmask_b32_e32 v0, v210, v0, vcc
	v_lshlrev_b32_e32 v84, 2, v0
	v_xor_b32_e32 v0, 16, v210
	s_addc_u32 s45, s11, s31
	s_ashr_i32 s27, s26, 31
	v_cmp_lt_i32_e32 vcc, v0, v250
	s_lshl_b64 s[46:47], s[26:27], 12
	s_lshl_b64 s[4:5], s[4:5], 11
	v_readlane_b32 s12, v254, 26
	v_cndmask_b32_e32 v0, v210, v0, vcc
	s_add_u32 s25, s12, s78
	v_readlane_b32 s12, v254, 27
	v_lshlrev_b32_e32 v85, 2, v0
	v_xor_b32_e32 v0, 32, v210
	s_addc_u32 s30, s12, s79
	v_cmp_lt_i32_e32 vcc, v0, v250
	s_add_u32 s4, s25, s4
	v_lshlrev_b32_e32 v148, 3, v152
	v_cndmask_b32_e32 v0, v210, v0, vcc
	s_addc_u32 s5, s30, s5
	v_lshlrev_b32_e32 v86, 2, v0
	v_lshl_add_u64 v[76:77], s[4:5], 0, v[148:149]
	s_lshl_b64 s[48:49], s[26:27], 11
	global_load_dwordx4 v[156:159], v[66:67], off
	global_load_dwordx4 v[160:163], v[66:67], off offset:1024
	global_load_dwordx4 v[164:167], v[66:67], off offset:2048
	global_load_dwordx4 v[168:171], v[66:67], off offset:3072
	s_add_u32 s4, s44, 0x1000
	s_addc_u32 s5, s45, 0
	s_add_u32 s34, s44, 0x2000
	s_addc_u32 s35, s45, 0
	s_add_u32 s54, s44, 0x3000
	s_addc_u32 s55, s45, 0
	global_load_dwordx4 v[0:3], v74, s[44:45]
	global_load_dwordx4 v[4:7], v74, s[44:45] offset:1024
	global_load_dwordx4 v[8:11], v74, s[44:45] offset:2048
	global_load_dwordx4 v[12:15], v74, s[44:45] offset:3072
	global_load_dwordx4 v[16:19], v74, s[4:5]
	global_load_dwordx4 v[20:23], v74, s[4:5] offset:1024
	global_load_dwordx4 v[24:27], v74, s[4:5] offset:2048
	global_load_dwordx4 v[28:31], v74, s[4:5] offset:3072
	global_load_dwordx4 v[32:35], v74, s[34:35]
	global_load_dwordx4 v[36:39], v74, s[34:35] offset:1024
	global_load_dwordx4 v[40:43], v74, s[34:35] offset:2048
	global_load_dwordx4 v[44:47], v74, s[34:35] offset:3072
	global_load_dwordx4 v[48:51], v74, s[54:55]
	global_load_dwordx4 v[52:55], v74, s[54:55] offset:1024
	global_load_dwordx4 v[56:59], v74, s[54:55] offset:2048
	global_load_dwordx4 v[60:63], v74, s[54:55] offset:3072
	s_branch .LBB0_317
.LBB0_317:
	s_add_i32 s30, s20, 0xffff
	s_ashr_i32 s30, s30, 12
	s_mul_hi_i32 s31, s30, 0x6000
	s_mulk_i32 s30, 0x6000
	s_add_u32 s50, s16, s30
	s_addc_u32 s51, s17, s31
	s_add_u32 s50, s50, 0x3000
	s_addc_u32 s51, s51, 0
	s_add_u32 s52, s50, 0x1000
	s_addc_u32 s53, s51, 0
	global_load_dwordx4 v[110:113], v74, s[50:51]
	global_load_dwordx4 v[114:117], v74, s[50:51] offset:1024
	global_load_dwordx4 v[118:121], v74, s[50:51] offset:2048
	global_load_dwordx4 v[122:125], v74, s[50:51] offset:3072
	global_load_dwordx4 v[126:129], v74, s[52:53]
	global_load_dwordx4 v[130:133], v74, s[52:53] offset:1024
	global_load_dwordx4 v[134:137], v74, s[52:53] offset:2048
	global_load_dwordx4 v[138:141], v74, s[52:53] offset:3072
	s_add_i32 s27, s20, s26
	s_add_i32 s27, s27, 0xffff
	s_cmp_gt_i32 s27, 0xffff
	s_cselect_b32 s30, 0, s46
	s_cselect_b32 s31, 0, s47
	s_add_u32 s44, s44, s30
	s_addc_u32 s45, s45, s31
	s_add_u32 s4, s44, 0x1000
	s_addc_u32 s5, s45, 0
	s_add_u32 s34, s44, 0x2000
	s_addc_u32 s35, s45, 0
	s_add_u32 s54, s44, 0x3000
	s_addc_u32 s55, s45, 0
	s_mov_b32 s30, 0xfffff000
	s_mov_b32 s31, -1
	v_mov_b32_e32 v178, s68
	v_lshl_add_u64 v[198:199], v[76:77], 0, s[30:31]
	s_waitcnt vmcnt(20)
	v_mul_f32_e32 v176, v1, v1
	v_mul_f32_e32 v177, v3, v3
	v_fmac_f32_e32 v176, v0, v0
	v_fmac_f32_e32 v177, v2, v2
	v_add_f32_e32 v172, v176, v177
	v_mul_f32_e32 v176, v5, v5
	v_mul_f32_e32 v177, v7, v7
	v_fmac_f32_e32 v176, v4, v4
	v_fmac_f32_e32 v177, v6, v6
	v_add_f32_e32 v176, v176, v177
	v_add_f32_e32 v172, v172, v176
	v_mul_f32_e32 v176, v9, v9
	v_mul_f32_e32 v177, v11, v11
	v_fmac_f32_e32 v176, v8, v8
	v_fmac_f32_e32 v177, v10, v10
	v_add_f32_e32 v176, v176, v177
	v_add_f32_e32 v172, v172, v176
	v_mul_f32_e32 v176, v13, v13
	v_mul_f32_e32 v177, v15, v15
	v_fmac_f32_e32 v176, v12, v12
	v_fmac_f32_e32 v177, v14, v14
	v_add_f32_e32 v176, v176, v177
	v_add_f32_e32 v172, v172, v176
	s_waitcnt vmcnt(16)
; DI unsigned pk2(float lo, float hi) { f32x2 v = {lo, hi}; bf16x2_t b = __builtin_convertvector(v, bf16x2_t); return __builtin_bit_cast(unsigned, b); }
; DI void normmod_phase(const float* xl, const float* xc, const float* g, const float* modl  , int cshift, int cscale, bf16_t* H, int nrows, int gw, int NGW, int lane,
;                       const float* part  , const float* pgate  , float* xc_out) {
;     ...
;             ss += (v[j][0] * v[j][0] + v[j][1] * v[j][1]) + (v[j][2] * v[j][2] + v[j][3] * v[j][3]); }
;         return ss; };
;     auto st = [&](const int row, const f32x4 (&v)[4], const float rs) __attribute__((always_inline)) {
;         const float* mp = modl + (size_t)((row < ML) ? (row >> 12) : 16) * 6144;
; #pragma unroll
;         for (int j = 0; j < 4; ++j) { const int c = lane * 4 + 256 * j;
;             const f32x4 gg = *(const f32x4*)(g + c), sh = *(const f32x4*)(mp + cshift * 1024 + c), scl = *(const f32x4*)(mp + cscale * 1024 + c);
;             const f32x4 y = (v[j] * rs) * gg * (scl + 1.f) + sh;
;             u32x2 o; o.x = pk2(y[0], y[1]); o.y = pk2(y[2], y[3]);
;             *(u32x2*)(H + (size_t)row * D + c) = o; } };
;     for (int row = gw * 4; row < (nrows < ML ? nrows : ML); row += NGW * 4) {
;         f32x4 vA[4], vB[4], vC[4], vD[4];
;         float sA = ld(row, vA), sB = ld(row + 1, vB), sC = ld(row + 2, vC), sD = ld(row + 3, vD);
; #pragma unroll
;         for (int o = 1; o < 64; o <<= 1) { sA += __shfl_xor(sA, o); sB += __shfl_xor(sB, o); sC += __shfl_xor(sC, o); sD += __shfl_xor(sD, o); }
;         st(row, vA, rsqrtf(sA * (1.f / D) + EPS)); st(row + 1, vB, rsqrtf(sB * (1.f / D) + EPS));
	v_mul_f32_e32 v176, v17, v17
	v_mul_f32_e32 v177, v19, v19
	v_fmac_f32_e32 v176, v16, v16
	v_fmac_f32_e32 v177, v18, v18
	v_add_f32_e32 v173, v176, v177
	v_mul_f32_e32 v176, v21, v21
	v_mul_f32_e32 v177, v23, v23
	v_fmac_f32_e32 v176, v20, v20
	v_fmac_f32_e32 v177, v22, v22
	v_add_f32_e32 v176, v176, v177
	v_add_f32_e32 v173, v173, v176
	v_mul_f32_e32 v176, v25, v25
	v_mul_f32_e32 v177, v27, v27
	v_fmac_f32_e32 v176, v24, v24
	v_fmac_f32_e32 v177, v26, v26
	v_add_f32_e32 v176, v176, v177
	v_add_f32_e32 v173, v173, v176
	v_mul_f32_e32 v176, v29, v29
	v_mul_f32_e32 v177, v31, v31
	v_fmac_f32_e32 v176, v28, v28
	v_fmac_f32_e32 v177, v30, v30
	v_add_f32_e32 v176, v176, v177
	v_add_f32_e32 v173, v173, v176
	s_waitcnt vmcnt(12)
	v_mul_f32_e32 v176, v33, v33
	v_mul_f32_e32 v177, v35, v35
	v_fmac_f32_e32 v176, v32, v32
	v_fmac_f32_e32 v177, v34, v34
	v_add_f32_e32 v174, v176, v177
	v_mul_f32_e32 v176, v37, v37
	v_mul_f32_e32 v177, v39, v39
	v_fmac_f32_e32 v176, v36, v36
	v_fmac_f32_e32 v177, v38, v38
	v_add_f32_e32 v176, v176, v177
	v_add_f32_e32 v174, v174, v176
	v_mul_f32_e32 v176, v41, v41
	v_mul_f32_e32 v177, v43, v43
	v_fmac_f32_e32 v176, v40, v40
	v_fmac_f32_e32 v177, v42, v42
	v_add_f32_e32 v176, v176, v177
	v_add_f32_e32 v174, v174, v176
	v_mul_f32_e32 v176, v45, v45
	v_mul_f32_e32 v177, v47, v47
	v_fmac_f32_e32 v176, v44, v44
	v_fmac_f32_e32 v177, v46, v46
	v_add_f32_e32 v176, v176, v177
	v_add_f32_e32 v174, v174, v176
	s_waitcnt vmcnt(8)
	v_mul_f32_e32 v176, v49, v49
	v_mul_f32_e32 v177, v51, v51
	v_fmac_f32_e32 v176, v48, v48
	v_fmac_f32_e32 v177, v50, v50
	v_add_f32_e32 v175, v176, v177
	v_mul_f32_e32 v176, v53, v53
	v_mul_f32_e32 v177, v55, v55
	v_fmac_f32_e32 v176, v52, v52
	v_fmac_f32_e32 v177, v54, v54
	v_add_f32_e32 v176, v176, v177
	v_add_f32_e32 v175, v175, v176
	v_mul_f32_e32 v176, v57, v57
	v_mul_f32_e32 v177, v59, v59
	v_fmac_f32_e32 v176, v56, v56
	v_fmac_f32_e32 v177, v58, v58
	v_add_f32_e32 v176, v176, v177
	v_add_f32_e32 v175, v175, v176
	v_mul_f32_e32 v176, v61, v61
	v_mul_f32_e32 v177, v63, v63
	v_fmac_f32_e32 v176, v60, v60
	v_fmac_f32_e32 v177, v62, v62
	v_add_f32_e32 v176, v176, v177
	v_add_f32_e32 v175, v175, v176
	ds_bpermute_b32 v184, v81, v172
	ds_bpermute_b32 v185, v81, v173
	ds_bpermute_b32 v186, v81, v174
	ds_bpermute_b32 v187, v81, v175
	s_waitcnt lgkmcnt(0)
	v_pk_add_f32 v[172:173], v[172:173], v[184:185]
	v_pk_add_f32 v[174:175], v[174:175], v[186:187]
	ds_bpermute_b32 v184, v82, v172
	ds_bpermute_b32 v185, v82, v173
	ds_bpermute_b32 v186, v82, v174
	ds_bpermute_b32 v187, v82, v175
	s_waitcnt lgkmcnt(0)
	v_pk_add_f32 v[172:173], v[172:173], v[184:185]
	v_pk_add_f32 v[174:175], v[174:175], v[186:187]
	ds_bpermute_b32 v184, v83, v172
	ds_bpermute_b32 v185, v83, v173
	ds_bpermute_b32 v186, v83, v174
	ds_bpermute_b32 v187, v83, v175
	s_waitcnt lgkmcnt(0)
	v_pk_add_f32 v[172:173], v[172:173], v[184:185]
	v_pk_add_f32 v[174:175], v[174:175], v[186:187]
	ds_bpermute_b32 v184, v84, v172
	ds_bpermute_b32 v185, v84, v173
	ds_bpermute_b32 v186, v84, v174
	ds_bpermute_b32 v187, v84, v175
	s_waitcnt lgkmcnt(0)
	v_pk_add_f32 v[172:173], v[172:173], v[184:185]
	v_pk_add_f32 v[174:175], v[174:175], v[186:187]
	ds_bpermute_b32 v184, v85, v172
	ds_bpermute_b32 v185, v85, v173
	ds_bpermute_b32 v186, v85, v174
	ds_bpermute_b32 v187, v85, v175
	s_waitcnt lgkmcnt(0)
	v_pk_add_f32 v[172:173], v[172:173], v[184:185]
	v_pk_add_f32 v[174:175], v[174:175], v[186:187]
	ds_bpermute_b32 v184, v86, v172
	ds_bpermute_b32 v185, v86, v173
	ds_bpermute_b32 v186, v86, v174
	ds_bpermute_b32 v187, v86, v175
	s_waitcnt lgkmcnt(0)
	v_pk_add_f32 v[172:173], v[172:173], v[184:185]
	v_pk_add_f32 v[174:175], v[174:175], v[186:187]
	v_fma_f32 v172, v172, s66, v178
	v_fma_f32 v173, v173, s66, v178
	v_fma_f32 v174, v174, s66, v178
	v_fma_f32 v175, v175, s66, v178
	v_mul_f32_e32 v184, 0x4b800000, v172
	v_mul_f32_e32 v185, 0x4b800000, v173
	v_mul_f32_e32 v186, 0x4b800000, v174
	v_mul_f32_e32 v187, 0x4b800000, v175
	s_waitcnt vmcnt(0)
	v_cmp_gt_f32_e64 s[50:51], s62, v172
	v_cmp_gt_f32_e64 s[52:53], s62, v173
	v_cmp_gt_f32_e64 s[30:31], s62, v174
	v_cmp_gt_f32_e32 vcc, s62, v175
	s_nop 1
	v_cndmask_b32_e64 v172, v172, v184, s[50:51]
	v_cndmask_b32_e64 v173, v173, v185, s[52:53]
	v_cndmask_b32_e64 v174, v174, v186, s[30:31]
	v_cndmask_b32_e32 v175, v175, v187, vcc
	v_rsq_f32_e32 v172, v172
	v_rsq_f32_e32 v173, v173
	v_rsq_f32_e32 v174, v174
	v_rsq_f32_e32 v175, v175
	s_nop 0
	v_mul_f32_e32 v184, 0x45800000, v172
	v_mul_f32_e32 v185, 0x45800000, v173
	v_mul_f32_e32 v186, 0x45800000, v174
	v_mul_f32_e32 v187, 0x45800000, v175
	v_cndmask_b32_e64 v188, v172, v184, s[50:51]
	v_cndmask_b32_e64 v190, v173, v185, s[52:53]
	v_cndmask_b32_e64 v192, v174, v186, s[30:31]
	v_cndmask_b32_e32 v194, v175, v187, vcc
	v_pk_add_f32 v[126:127], v[126:127], 1.0 op_sel_hi:[1,0]
	v_pk_add_f32 v[128:129], v[128:129], 1.0 op_sel_hi:[1,0]
	v_pk_add_f32 v[130:131], v[130:131], 1.0 op_sel_hi:[1,0]
	v_pk_add_f32 v[132:133], v[132:133], 1.0 op_sel_hi:[1,0]
	v_pk_add_f32 v[134:135], v[134:135], 1.0 op_sel_hi:[1,0]
	v_pk_add_f32 v[136:137], v[136:137], 1.0 op_sel_hi:[1,0]
	v_pk_add_f32 v[138:139], v[138:139], 1.0 op_sel_hi:[1,0]
	v_pk_add_f32 v[140:141], v[140:141], 1.0 op_sel_hi:[1,0]
	v_pk_mul_f32 v[0:1], v[0:1], v[188:189] op_sel_hi:[1,0]
	v_pk_mul_f32 v[2:3], v[2:3], v[188:189] op_sel_hi:[1,0]
	v_pk_mul_f32 v[0:1], v[156:157], v[0:1]
	v_pk_mul_f32 v[2:3], v[158:159], v[2:3]
	v_pk_fma_f32 v[0:1], v[126:127], v[0:1], v[110:111]
	v_pk_fma_f32 v[2:3], v[128:129], v[2:3], v[112:113]
	v_cvt_pk_bf16_f32 v0, v0, v1
	v_cvt_pk_bf16_f32 v1, v2, v3
	global_store_dwordx2 v[198:199], v[0:1], off offset:-3584
; DI unsigned pk2(float lo, float hi) { f32x2 v = {lo, hi}; bf16x2_t b = __builtin_convertvector(v, bf16x2_t); return __builtin_bit_cast(unsigned, b); }
; DI void normmod_phase(const float* xl, const float* xc, const float* g, const float* modl  , int cshift, int cscale, bf16_t* H, int nrows, int gw, int NGW, int lane,
;                       const float* part  , const float* pgate  , float* xc_out) {
;     ...
;     auto st = [&](const int row, const f32x4 (&v)[4], const float rs) __attribute__((always_inline)) {
;         const float* mp = modl + (size_t)((row < ML) ? (row >> 12) : 16) * 6144;
; #pragma unroll
;         for (int j = 0; j < 4; ++j) { const int c = lane * 4 + 256 * j;
;             const f32x4 gg = *(const f32x4*)(g + c), sh = *(const f32x4*)(mp + cshift * 1024 + c), scl = *(const f32x4*)(mp + cscale * 1024 + c);
;             const f32x4 y = (v[j] * rs) * gg * (scl + 1.f) + sh;
;             u32x2 o; o.x = pk2(y[0], y[1]); o.y = pk2(y[2], y[3]);
;             *(u32x2*)(H + (size_t)row * D + c) = o; } };
;     ...
;         float sA = ld(row, vA), sB = ld(row + 1, vB), sC = ld(row + 2, vC), sD = ld(row + 3, vD);
	v_pk_mul_f32 v[4:5], v[4:5], v[188:189] op_sel_hi:[1,0]
	v_pk_mul_f32 v[6:7], v[6:7], v[188:189] op_sel_hi:[1,0]
	v_pk_mul_f32 v[4:5], v[160:161], v[4:5]
	v_pk_mul_f32 v[6:7], v[162:163], v[6:7]
	v_pk_fma_f32 v[4:5], v[130:131], v[4:5], v[114:115]
	v_pk_fma_f32 v[6:7], v[132:133], v[6:7], v[116:117]
	v_cvt_pk_bf16_f32 v4, v4, v5
	v_cvt_pk_bf16_f32 v5, v6, v7
	global_store_dwordx2 v[198:199], v[4:5], off offset:-3072
	v_pk_mul_f32 v[8:9], v[8:9], v[188:189] op_sel_hi:[1,0]
	v_pk_mul_f32 v[10:11], v[10:11], v[188:189] op_sel_hi:[1,0]
	v_pk_mul_f32 v[8:9], v[164:165], v[8:9]
	v_pk_mul_f32 v[10:11], v[166:167], v[10:11]
	v_pk_fma_f32 v[8:9], v[134:135], v[8:9], v[118:119]
	v_pk_fma_f32 v[10:11], v[136:137], v[10:11], v[120:121]
	v_cvt_pk_bf16_f32 v8, v8, v9
	v_cvt_pk_bf16_f32 v9, v10, v11
	global_store_dwordx2 v[198:199], v[8:9], off offset:-2560
	v_pk_mul_f32 v[12:13], v[12:13], v[188:189] op_sel_hi:[1,0]
	v_pk_mul_f32 v[14:15], v[14:15], v[188:189] op_sel_hi:[1,0]
	v_pk_mul_f32 v[12:13], v[168:169], v[12:13]
	v_pk_mul_f32 v[14:15], v[170:171], v[14:15]
	v_pk_fma_f32 v[12:13], v[138:139], v[12:13], v[122:123]
	v_pk_fma_f32 v[14:15], v[140:141], v[14:15], v[124:125]
	v_cvt_pk_bf16_f32 v12, v12, v13
	v_cvt_pk_bf16_f32 v13, v14, v15
	global_store_dwordx2 v[198:199], v[12:13], off offset:-2048
	global_load_dwordx4 v[0:3], v74, s[44:45]
	global_load_dwordx4 v[4:7], v74, s[44:45] offset:1024
	global_load_dwordx4 v[8:11], v74, s[44:45] offset:2048
	global_load_dwordx4 v[12:15], v74, s[44:45] offset:3072
	v_pk_mul_f32 v[16:17], v[16:17], v[190:191] op_sel_hi:[1,0]
	v_pk_mul_f32 v[18:19], v[18:19], v[190:191] op_sel_hi:[1,0]
	v_pk_mul_f32 v[16:17], v[156:157], v[16:17]
	v_pk_mul_f32 v[18:19], v[158:159], v[18:19]
	v_pk_fma_f32 v[16:17], v[126:127], v[16:17], v[110:111]
	v_pk_fma_f32 v[18:19], v[128:129], v[18:19], v[112:113]
	v_cvt_pk_bf16_f32 v16, v16, v17
	v_cvt_pk_bf16_f32 v17, v18, v19
	global_store_dwordx2 v[198:199], v[16:17], off offset:-1536
	v_pk_mul_f32 v[20:21], v[20:21], v[190:191] op_sel_hi:[1,0]
	v_pk_mul_f32 v[22:23], v[22:23], v[190:191] op_sel_hi:[1,0]
	v_pk_mul_f32 v[20:21], v[160:161], v[20:21]
	v_pk_mul_f32 v[22:23], v[162:163], v[22:23]
	v_pk_fma_f32 v[20:21], v[130:131], v[20:21], v[114:115]
	v_pk_fma_f32 v[22:23], v[132:133], v[22:23], v[116:117]
	v_cvt_pk_bf16_f32 v20, v20, v21
	v_cvt_pk_bf16_f32 v21, v22, v23
	global_store_dwordx2 v[198:199], v[20:21], off offset:-1024
	v_pk_mul_f32 v[24:25], v[24:25], v[190:191] op_sel_hi:[1,0]
	v_pk_mul_f32 v[26:27], v[26:27], v[190:191] op_sel_hi:[1,0]
	v_pk_mul_f32 v[24:25], v[164:165], v[24:25]
	v_pk_mul_f32 v[26:27], v[166:167], v[26:27]
	v_pk_fma_f32 v[24:25], v[134:135], v[24:25], v[118:119]
	v_pk_fma_f32 v[26:27], v[136:137], v[26:27], v[120:121]
	v_cvt_pk_bf16_f32 v24, v24, v25
	v_cvt_pk_bf16_f32 v25, v26, v27
	global_store_dwordx2 v[198:199], v[24:25], off offset:-512
	v_pk_mul_f32 v[28:29], v[28:29], v[190:191] op_sel_hi:[1,0]
	v_pk_mul_f32 v[30:31], v[30:31], v[190:191] op_sel_hi:[1,0]
	v_pk_mul_f32 v[28:29], v[168:169], v[28:29]
	v_pk_mul_f32 v[30:31], v[170:171], v[30:31]
	v_pk_fma_f32 v[28:29], v[138:139], v[28:29], v[122:123]
	v_pk_fma_f32 v[30:31], v[140:141], v[30:31], v[124:125]
	v_cvt_pk_bf16_f32 v28, v28, v29
	v_cvt_pk_bf16_f32 v29, v30, v31
	global_store_dwordx2 v[76:77], v[28:29], off offset:-4096
	global_load_dwordx4 v[16:19], v74, s[4:5]
	global_load_dwordx4 v[20:23], v74, s[4:5] offset:1024
	global_load_dwordx4 v[24:27], v74, s[4:5] offset:2048
	global_load_dwordx4 v[28:31], v74, s[4:5] offset:3072
	v_pk_mul_f32 v[32:33], v[32:33], v[192:193] op_sel_hi:[1,0]
	v_pk_mul_f32 v[34:35], v[34:35], v[192:193] op_sel_hi:[1,0]
	v_pk_mul_f32 v[32:33], v[156:157], v[32:33]
	v_pk_mul_f32 v[34:35], v[158:159], v[34:35]
	v_pk_fma_f32 v[32:33], v[126:127], v[32:33], v[110:111]
	v_pk_fma_f32 v[34:35], v[128:129], v[34:35], v[112:113]
; DI unsigned pk2(float lo, float hi) { f32x2 v = {lo, hi}; bf16x2_t b = __builtin_convertvector(v, bf16x2_t); return __builtin_bit_cast(unsigned, b); }
; DI void normmod_phase(const float* xl, const float* xc, const float* g, const float* modl  , int cshift, int cscale, bf16_t* H, int nrows, int gw, int NGW, int lane,
;                       const float* part  , const float* pgate  , float* xc_out) {
;     ...
;     auto st = [&](const int row, const f32x4 (&v)[4], const float rs) __attribute__((always_inline)) {
;         const float* mp = modl + (size_t)((row < ML) ? (row >> 12) : 16) * 6144;
; #pragma unroll
;         for (int j = 0; j < 4; ++j) { const int c = lane * 4 + 256 * j;
;             const f32x4 gg = *(const f32x4*)(g + c), sh = *(const f32x4*)(mp + cshift * 1024 + c), scl = *(const f32x4*)(mp + cscale * 1024 + c);
;             const f32x4 y = (v[j] * rs) * gg * (scl + 1.f) + sh;
;             u32x2 o; o.x = pk2(y[0], y[1]); o.y = pk2(y[2], y[3]);
;             *(u32x2*)(H + (size_t)row * D + c) = o; } };
;     for (int row = gw * 4; row < (nrows < ML ? nrows : ML); row += NGW * 4) {
	v_cvt_pk_bf16_f32 v32, v32, v33
	v_cvt_pk_bf16_f32 v33, v34, v35
	global_store_dwordx2 v[76:77], v[32:33], off offset:-3584
	v_pk_mul_f32 v[36:37], v[36:37], v[192:193] op_sel_hi:[1,0]
	v_pk_mul_f32 v[38:39], v[38:39], v[192:193] op_sel_hi:[1,0]
	v_pk_mul_f32 v[36:37], v[160:161], v[36:37]
	v_pk_mul_f32 v[38:39], v[162:163], v[38:39]
	v_pk_fma_f32 v[36:37], v[130:131], v[36:37], v[114:115]
	v_pk_fma_f32 v[38:39], v[132:133], v[38:39], v[116:117]
	v_cvt_pk_bf16_f32 v36, v36, v37
	v_cvt_pk_bf16_f32 v37, v38, v39
	global_store_dwordx2 v[76:77], v[36:37], off offset:-3072
	v_pk_mul_f32 v[40:41], v[40:41], v[192:193] op_sel_hi:[1,0]
	v_pk_mul_f32 v[42:43], v[42:43], v[192:193] op_sel_hi:[1,0]
	v_pk_mul_f32 v[40:41], v[164:165], v[40:41]
	v_pk_mul_f32 v[42:43], v[166:167], v[42:43]
	v_pk_fma_f32 v[40:41], v[134:135], v[40:41], v[118:119]
	v_pk_fma_f32 v[42:43], v[136:137], v[42:43], v[120:121]
	v_cvt_pk_bf16_f32 v40, v40, v41
	v_cvt_pk_bf16_f32 v41, v42, v43
	global_store_dwordx2 v[76:77], v[40:41], off offset:-2560
	v_pk_mul_f32 v[44:45], v[44:45], v[192:193] op_sel_hi:[1,0]
	v_pk_mul_f32 v[46:47], v[46:47], v[192:193] op_sel_hi:[1,0]
	v_pk_mul_f32 v[44:45], v[168:169], v[44:45]
	v_pk_mul_f32 v[46:47], v[170:171], v[46:47]
	v_pk_fma_f32 v[44:45], v[138:139], v[44:45], v[122:123]
	v_pk_fma_f32 v[46:47], v[140:141], v[46:47], v[124:125]
	v_cvt_pk_bf16_f32 v44, v44, v45
	v_cvt_pk_bf16_f32 v45, v46, v47
	global_store_dwordx2 v[76:77], v[44:45], off offset:-2048
	global_load_dwordx4 v[32:35], v74, s[34:35]
	global_load_dwordx4 v[36:39], v74, s[34:35] offset:1024
	global_load_dwordx4 v[40:43], v74, s[34:35] offset:2048
	global_load_dwordx4 v[44:47], v74, s[34:35] offset:3072
	v_pk_mul_f32 v[48:49], v[48:49], v[194:195] op_sel_hi:[1,0]
	v_pk_mul_f32 v[50:51], v[50:51], v[194:195] op_sel_hi:[1,0]
	v_pk_mul_f32 v[48:49], v[156:157], v[48:49]
	v_pk_mul_f32 v[50:51], v[158:159], v[50:51]
	v_pk_fma_f32 v[48:49], v[126:127], v[48:49], v[110:111]
	v_pk_fma_f32 v[50:51], v[128:129], v[50:51], v[112:113]
	v_cvt_pk_bf16_f32 v48, v48, v49
	v_cvt_pk_bf16_f32 v49, v50, v51
	global_store_dwordx2 v[76:77], v[48:49], off offset:-1536
	v_pk_mul_f32 v[52:53], v[52:53], v[194:195] op_sel_hi:[1,0]
	v_pk_mul_f32 v[54:55], v[54:55], v[194:195] op_sel_hi:[1,0]
	v_pk_mul_f32 v[52:53], v[160:161], v[52:53]
	v_pk_mul_f32 v[54:55], v[162:163], v[54:55]
	v_pk_fma_f32 v[52:53], v[130:131], v[52:53], v[114:115]
	v_pk_fma_f32 v[54:55], v[132:133], v[54:55], v[116:117]
	v_cvt_pk_bf16_f32 v52, v52, v53
	v_cvt_pk_bf16_f32 v53, v54, v55
	global_store_dwordx2 v[76:77], v[52:53], off offset:-1024
	v_pk_mul_f32 v[56:57], v[56:57], v[194:195] op_sel_hi:[1,0]
	v_pk_mul_f32 v[58:59], v[58:59], v[194:195] op_sel_hi:[1,0]
	v_pk_mul_f32 v[56:57], v[164:165], v[56:57]
	v_pk_mul_f32 v[58:59], v[166:167], v[58:59]
	v_pk_fma_f32 v[56:57], v[134:135], v[56:57], v[118:119]
	v_pk_fma_f32 v[58:59], v[136:137], v[58:59], v[120:121]
	v_cvt_pk_bf16_f32 v56, v56, v57
	v_cvt_pk_bf16_f32 v57, v58, v59
	global_store_dwordx2 v[76:77], v[56:57], off offset:-512
	v_pk_mul_f32 v[60:61], v[60:61], v[194:195] op_sel_hi:[1,0]
	v_pk_mul_f32 v[62:63], v[62:63], v[194:195] op_sel_hi:[1,0]
	v_pk_mul_f32 v[60:61], v[168:169], v[60:61]
	v_pk_mul_f32 v[62:63], v[170:171], v[62:63]
	v_pk_fma_f32 v[60:61], v[138:139], v[60:61], v[122:123]
	v_pk_fma_f32 v[62:63], v[140:141], v[62:63], v[124:125]
	v_cvt_pk_bf16_f32 v60, v60, v61
	v_cvt_pk_bf16_f32 v61, v62, v63
	global_store_dwordx2 v[76:77], v[60:61], off
	global_load_dwordx4 v[48:51], v74, s[54:55]
	global_load_dwordx4 v[52:55], v74, s[54:55] offset:1024
	global_load_dwordx4 v[56:59], v74, s[54:55] offset:2048
	global_load_dwordx4 v[60:63], v74, s[54:55] offset:3072
	s_add_i32 s20, s20, s26
	v_lshl_add_u64 v[76:77], v[76:77], 0, s[48:49]
	s_add_i32 s4, s20, 0xffff
	s_cmp_gt_i32 s4, 0xffff
	s_cbranch_scc0 .LBB0_317
	s_waitcnt vmcnt(0)

; DI void normmod_phase(const float* xl, const float* xc, const float* g, const float* modl  , int cshift, int cscale, bf16_t* H, int nrows, int gw, int NGW, int lane,
;                       const float* part  , const float* pgate  , float* xc_out) {
;     auto ld = [&](const int row, f32x4 (&v)[4]) __attribute__((always_inline)) -> float {
;         const bool lat = row < ML;
;         const float* xr = lat ? xl + (size_t)row * D : xc + (size_t)(row - ML) * D;
;         float ss = 0.f;
; #pragma unroll
;         for (int j = 0; j < 4; ++j) { v[j] = *(const f32x4*)(xr + lane * 4 + 256 * j);
;             if (part && !lat) {
;                 const size_t po = (size_t)(row - ML) * D + lane * 4 + 256 * j;
;                 const f32x4 p0 = *(const f32x4*)(part + po), p1 = *(const f32x4*)(part + (size_t)MC * D + po), p2 = *(const f32x4*)(part + (size_t)2 * MC * D + po), p3 = *(const f32x4*)(part + (size_t)3 * MC * D + po);
;                 v[j] = v[j] + *(const f32x4*)(pgate + lane * 4 + 256 * j) * ((p0 + p1) + (p2 + p3));
;                 *(f32x4*)(xc_out + po) = v[j]; }
;             ss += (v[j][0] * v[j][0] + v[j][1] * v[j][1]) + (v[j][2] * v[j][2] + v[j][3] * v[j][3]); }
;         return ss; };
;     auto st = [&](const int row, const f32x4 (&v)[4], const float rs) __attribute__((always_inline)) {
;         const float* mp = modl + (size_t)((row < ML) ? (row >> 12) : 16) * 6144;
; #pragma unroll
;         for (int j = 0; j < 4; ++j) { const int c = lane * 4 + 256 * j;
;             const f32x4 gg = *(const f32x4*)(g + c), sh = *(const f32x4*)(mp + cshift * 1024 + c), scl = *(const f32x4*)(mp + cscale * 1024 + c);
;             const f32x4 y = (v[j] * rs) * gg * (scl + 1.f) + sh;
;             u32x2 o; o.x = pk2(y[0], y[1]); o.y = pk2(y[2], y[3]);
;             *(u32x2*)(H + (size_t)row * D + c) = o; } };
;     for (int row = gw * 4; row < (nrows < ML ? nrows : ML); row += NGW * 4) {
;         f32x4 vA[4], vB[4], vC[4], vD[4];
;         float sA = ld(row, vA), sB = ld(row + 1, vB), sC = ld(row + 2, vC), sD = ld(row + 3, vD);
; #pragma unroll
;         for (int o = 1; o < 64; o <<= 1) { sA += __shfl_xor(sA, o); sB += __shfl_xor(sB, o); sC += __shfl_xor(sC, o); sD += __shfl_xor(sD, o); }
;         st(row, vA, rsqrtf(sA * (1.f / D) + EPS)); st(row + 1, vB, rsqrtf(sB * (1.f / D) + EPS));
.LBB0_553:
	s_andn2_b64 vcc, exec, s[4:5]
	s_cbranch_vccnz .LBB0_621
	s_lshl_b64 s[4:5], s[78:79], 3
	v_readlane_b32 s6, v253, 5
	v_readlane_b32 s7, v253, 6
	s_add_u32 s4, s6, s4
	s_addc_u32 s5, s7, s5
	s_load_dwordx2 s[4:5], s[4:5], 0x30
	s_lshl_b32 s6, s69, 12
	v_readlane_b32 s54, v253, 28
	v_readlane_b32 s55, v253, 29
	v_lshlrev_b32_e32 v69, 2, v152
	s_waitcnt lgkmcnt(0)
	s_add_u32 s4, s4, s6
	v_readlane_b32 s6, v253, 23
	s_addc_u32 s5, s5, 0
	v_readlane_b32 s7, v253, 24
	s_and_b64 s[6:7], s[6:7], exec
	s_cselect_b32 s23, 0, 0x15400000
	s_add_u32 s6, s84, 0x312dc000
	s_addc_u32 s7, s85, 0
	s_and_b64 s[8:9], s[54:55], exec
	s_cselect_b32 s24, 0, s6
	s_cselect_b32 s20, 0, s7
	s_add_u32 s8, s24, 0x1000000
	s_addc_u32 s9, s20, 0
	s_add_u32 s38, s24, 0x2000000
	s_addc_u32 s39, s20, 0
	s_add_u32 s40, s24, 0x3000000
	s_addc_u32 s41, s20, 0
	v_lshlrev_b32_e32 v76, 4, v152
	v_mov_b32_e32 v77, v149
	v_or_b32_e32 v68, 0x100, v69
	v_or_b32_e32 v70, 0x200, v69
	v_or_b32_e32 v72, 0x300, v69
	s_mov_b32 s56, s36
	s_cmpk_gt_i32 s36, 0x3fff
	v_lshl_add_u64 v[64:65], s[16:17], 0, v[76:77]
	v_lshl_add_u64 v[66:67], s[4:5], 0, v[76:77]
	v_lshlrev_b32_e32 v74, 3, v152
	v_lshlrev_b32_e32 v71, 2, v68
	v_lshlrev_b32_e32 v73, 2, v70
	v_lshlrev_b32_e32 v82, 2, v72
	s_movk_i32 s13, 0xf000
	s_mov_b32 s34, 0x3a800000
	s_mov_b32 s36, 0x358637bd
	s_cbranch_scc1 .LBB0_593
	s_waitcnt vmcnt(5)
	v_xor_b32_e32 v0, 1, v210
	v_cmp_lt_i32_e32 vcc, v0, v250
	s_lshl_b32 s5, s96, 5
	s_lshl_b32 s20, s37, 2
	v_cndmask_b32_e32 v0, v210, v0, vcc
	v_lshlrev_b32_e32 v83, 2, v0
	v_xor_b32_e32 v0, 2, v210
	s_lshl_b32 s4, s56, 2
	v_cmp_lt_i32_e32 vcc, v0, v250
	s_add_i32 s5, s5, s20
	s_add_i32 s20, s5, 0xffff0001
	v_cndmask_b32_e32 v0, v210, v0, vcc
	v_cmp_lt_i32_e32 vcc, v251, v250
	s_ashr_i32 s5, s4, 31
	s_lshl_b32 s26, s33, 5
	v_lshlrev_b32_e32 v84, 2, v0
	v_cndmask_b32_e32 v0, v210, v251, vcc
	s_lshl_b64 s[24:25], s[4:5], 12
	v_lshlrev_b32_e32 v85, 2, v0
	v_xor_b32_e32 v0, 8, v210
	s_add_u32 s42, s10, s24
	v_cmp_lt_i32_e32 vcc, v0, v250
	s_addc_u32 s43, s11, s25
	s_ashr_i32 s27, s26, 31
	v_cndmask_b32_e32 v0, v210, v0, vcc
	s_lshl_b64 s[44:45], s[26:27], 12
	s_lshl_b64 s[4:5], s[4:5], 11
	v_lshlrev_b32_e32 v86, 2, v0
	v_xor_b32_e32 v0, 16, v210
	s_add_u32 s4, s23, s4
	v_cmp_lt_i32_e32 vcc, v0, v250
	s_addc_u32 s5, 0, s5
	v_readlane_b32 s12, v254, 26
	v_cndmask_b32_e32 v0, v210, v0, vcc
	s_add_u32 s24, s12, s78
	v_readlane_b32 s12, v254, 27
	v_lshlrev_b32_e32 v87, 2, v0
	v_xor_b32_e32 v0, 32, v210
	s_addc_u32 s25, s12, s79
	v_cmp_lt_i32_e32 vcc, v0, v250
	s_add_u32 s4, s24, s4
	v_mov_b32_e32 v75, v149
	v_cndmask_b32_e32 v0, v210, v0, vcc
	s_addc_u32 s5, s25, s5
	v_lshlrev_b32_e32 v88, 2, v0
	v_lshl_add_u64 v[78:79], s[4:5], 0, v[74:75]
	s_lshl_b64 s[46:47], s[26:27], 11
	global_load_dwordx4 v[156:159], v[66:67], off
	global_load_dwordx4 v[160:163], v[66:67], off offset:1024
	global_load_dwordx4 v[164:167], v[66:67], off offset:2048
	global_load_dwordx4 v[168:171], v[66:67], off offset:3072
	s_add_u32 s4, s42, 0x1000
	s_addc_u32 s5, s43, 0
	s_add_u32 s24, s42, 0x2000
	s_addc_u32 s25, s43, 0
	s_add_u32 s48, s42, 0x3000
	s_addc_u32 s49, s43, 0
	global_load_dwordx4 v[0:3], v76, s[42:43]
	global_load_dwordx4 v[4:7], v76, s[42:43] offset:1024
	global_load_dwordx4 v[8:11], v76, s[42:43] offset:2048
	global_load_dwordx4 v[12:15], v76, s[42:43] offset:3072
	global_load_dwordx4 v[16:19], v76, s[4:5]
	global_load_dwordx4 v[20:23], v76, s[4:5] offset:1024
	global_load_dwordx4 v[24:27], v76, s[4:5] offset:2048
	global_load_dwordx4 v[28:31], v76, s[4:5] offset:3072
	global_load_dwordx4 v[32:35], v76, s[24:25]
	global_load_dwordx4 v[36:39], v76, s[24:25] offset:1024
	global_load_dwordx4 v[40:43], v76, s[24:25] offset:2048
	global_load_dwordx4 v[44:47], v76, s[24:25] offset:3072
	global_load_dwordx4 v[48:51], v76, s[48:49]
	global_load_dwordx4 v[52:55], v76, s[48:49] offset:1024
	global_load_dwordx4 v[56:59], v76, s[48:49] offset:2048
	global_load_dwordx4 v[60:63], v76, s[48:49] offset:3072
	s_branch .LBB0_557
.LBB0_557:
	s_add_i32 s30, s20, 0xffff
	s_ashr_i32 s30, s30, 12
	s_mul_hi_i32 s31, s30, 0x6000
	s_mulk_i32 s30, 0x6000
	s_add_u32 s50, s16, s30
	s_addc_u32 s51, s17, s31
	s_add_u32 s52, s50, 0x1000
	s_addc_u32 s53, s51, 0
	global_load_dwordx4 v[110:113], v76, s[50:51]
	global_load_dwordx4 v[114:117], v76, s[50:51] offset:1024
	global_load_dwordx4 v[118:121], v76, s[50:51] offset:2048
	global_load_dwordx4 v[122:125], v76, s[50:51] offset:3072
	global_load_dwordx4 v[126:129], v76, s[52:53]
	global_load_dwordx4 v[130:133], v76, s[52:53] offset:1024
	global_load_dwordx4 v[134:137], v76, s[52:53] offset:2048
	global_load_dwordx4 v[138:141], v76, s[52:53] offset:3072
	s_add_i32 s27, s20, s26
	s_add_i32 s27, s27, 0xffff
	s_cmp_gt_i32 s27, 0xffff
	s_cselect_b32 s30, 0, s44
	s_cselect_b32 s31, 0, s45
	s_add_u32 s42, s42, s30
	s_addc_u32 s43, s43, s31
	s_add_u32 s4, s42, 0x1000
	s_addc_u32 s5, s43, 0
	s_add_u32 s24, s42, 0x2000
	s_addc_u32 s25, s43, 0
	s_add_u32 s48, s42, 0x3000
	s_addc_u32 s49, s43, 0
	s_mov_b32 s30, 0xfffff000
	s_mov_b32 s31, -1
	v_mov_b32_e32 v178, s36
	v_lshl_add_u64 v[198:199], v[78:79], 0, s[30:31]
	s_waitcnt vmcnt(20)
	v_mul_f32_e32 v176, v1, v1
	v_mul_f32_e32 v177, v3, v3
	v_fmac_f32_e32 v176, v0, v0
	v_fmac_f32_e32 v177, v2, v2
	v_add_f32_e32 v172, v176, v177
	v_mul_f32_e32 v176, v5, v5
	v_mul_f32_e32 v177, v7, v7
	v_fmac_f32_e32 v176, v4, v4
	v_fmac_f32_e32 v177, v6, v6
	v_add_f32_e32 v176, v176, v177
	v_add_f32_e32 v172, v172, v176
	v_mul_f32_e32 v176, v9, v9
	v_mul_f32_e32 v177, v11, v11
	v_fmac_f32_e32 v176, v8, v8
	v_fmac_f32_e32 v177, v10, v10
	v_add_f32_e32 v176, v176, v177
	v_add_f32_e32 v172, v172, v176
	v_mul_f32_e32 v176, v13, v13
	v_mul_f32_e32 v177, v15, v15
	v_fmac_f32_e32 v176, v12, v12
	v_fmac_f32_e32 v177, v14, v14
	v_add_f32_e32 v176, v176, v177
	v_add_f32_e32 v172, v172, v176
	s_waitcnt vmcnt(16)
; DI unsigned pk2(float lo, float hi) { f32x2 v = {lo, hi}; bf16x2_t b = __builtin_convertvector(v, bf16x2_t); return __builtin_bit_cast(unsigned, b); }
; DI void normmod_phase(const float* xl, const float* xc, const float* g, const float* modl  , int cshift, int cscale, bf16_t* H, int nrows, int gw, int NGW, int lane,
;                       const float* part  , const float* pgate  , float* xc_out) {
;     ...
;             ss += (v[j][0] * v[j][0] + v[j][1] * v[j][1]) + (v[j][2] * v[j][2] + v[j][3] * v[j][3]); }
;         return ss; };
;     auto st = [&](const int row, const f32x4 (&v)[4], const float rs) __attribute__((always_inline)) {
;         const float* mp = modl + (size_t)((row < ML) ? (row >> 12) : 16) * 6144;
; #pragma unroll
;         for (int j = 0; j < 4; ++j) { const int c = lane * 4 + 256 * j;
;             const f32x4 gg = *(const f32x4*)(g + c), sh = *(const f32x4*)(mp + cshift * 1024 + c), scl = *(const f32x4*)(mp + cscale * 1024 + c);
;             const f32x4 y = (v[j] * rs) * gg * (scl + 1.f) + sh;
;             u32x2 o; o.x = pk2(y[0], y[1]); o.y = pk2(y[2], y[3]);
;             *(u32x2*)(H + (size_t)row * D + c) = o; } };
;     for (int row = gw * 4; row < (nrows < ML ? nrows : ML); row += NGW * 4) {
;         f32x4 vA[4], vB[4], vC[4], vD[4];
;         float sA = ld(row, vA), sB = ld(row + 1, vB), sC = ld(row + 2, vC), sD = ld(row + 3, vD);
; #pragma unroll
;         for (int o = 1; o < 64; o <<= 1) { sA += __shfl_xor(sA, o); sB += __shfl_xor(sB, o); sC += __shfl_xor(sC, o); sD += __shfl_xor(sD, o); }
;         st(row, vA, rsqrtf(sA * (1.f / D) + EPS)); st(row + 1, vB, rsqrtf(sB * (1.f / D) + EPS));
	v_mul_f32_e32 v176, v17, v17
	v_mul_f32_e32 v177, v19, v19
	v_fmac_f32_e32 v176, v16, v16
	v_fmac_f32_e32 v177, v18, v18
	v_add_f32_e32 v173, v176, v177
	v_mul_f32_e32 v176, v21, v21
	v_mul_f32_e32 v177, v23, v23
	v_fmac_f32_e32 v176, v20, v20
	v_fmac_f32_e32 v177, v22, v22
	v_add_f32_e32 v176, v176, v177
	v_add_f32_e32 v173, v173, v176
	v_mul_f32_e32 v176, v25, v25
	v_mul_f32_e32 v177, v27, v27
	v_fmac_f32_e32 v176, v24, v24
	v_fmac_f32_e32 v177, v26, v26
	v_add_f32_e32 v176, v176, v177
	v_add_f32_e32 v173, v173, v176
	v_mul_f32_e32 v176, v29, v29
	v_mul_f32_e32 v177, v31, v31
	v_fmac_f32_e32 v176, v28, v28
	v_fmac_f32_e32 v177, v30, v30
	v_add_f32_e32 v176, v176, v177
	v_add_f32_e32 v173, v173, v176
	s_waitcnt vmcnt(12)
	v_mul_f32_e32 v176, v33, v33
	v_mul_f32_e32 v177, v35, v35
	v_fmac_f32_e32 v176, v32, v32
	v_fmac_f32_e32 v177, v34, v34
	v_add_f32_e32 v174, v176, v177
	v_mul_f32_e32 v176, v37, v37
	v_mul_f32_e32 v177, v39, v39
	v_fmac_f32_e32 v176, v36, v36
	v_fmac_f32_e32 v177, v38, v38
	v_add_f32_e32 v176, v176, v177
	v_add_f32_e32 v174, v174, v176
	v_mul_f32_e32 v176, v41, v41
	v_mul_f32_e32 v177, v43, v43
	v_fmac_f32_e32 v176, v40, v40
	v_fmac_f32_e32 v177, v42, v42
	v_add_f32_e32 v176, v176, v177
	v_add_f32_e32 v174, v174, v176
	v_mul_f32_e32 v176, v45, v45
	v_mul_f32_e32 v177, v47, v47
	v_fmac_f32_e32 v176, v44, v44
	v_fmac_f32_e32 v177, v46, v46
	v_add_f32_e32 v176, v176, v177
	v_add_f32_e32 v174, v174, v176
	s_waitcnt vmcnt(8)
	v_mul_f32_e32 v176, v49, v49
	v_mul_f32_e32 v177, v51, v51
	v_fmac_f32_e32 v176, v48, v48
	v_fmac_f32_e32 v177, v50, v50
	v_add_f32_e32 v175, v176, v177
	v_mul_f32_e32 v176, v53, v53
	v_mul_f32_e32 v177, v55, v55
	v_fmac_f32_e32 v176, v52, v52
	v_fmac_f32_e32 v177, v54, v54
	v_add_f32_e32 v176, v176, v177
	v_add_f32_e32 v175, v175, v176
	v_mul_f32_e32 v176, v57, v57
	v_mul_f32_e32 v177, v59, v59
	v_fmac_f32_e32 v176, v56, v56
	v_fmac_f32_e32 v177, v58, v58
	v_add_f32_e32 v176, v176, v177
	v_add_f32_e32 v175, v175, v176
	v_mul_f32_e32 v176, v61, v61
	v_mul_f32_e32 v177, v63, v63
	v_fmac_f32_e32 v176, v60, v60
	v_fmac_f32_e32 v177, v62, v62
	v_add_f32_e32 v176, v176, v177
	v_add_f32_e32 v175, v175, v176
	ds_bpermute_b32 v184, v83, v172
	ds_bpermute_b32 v185, v83, v173
	ds_bpermute_b32 v186, v83, v174
	ds_bpermute_b32 v187, v83, v175
	s_waitcnt lgkmcnt(0)
	v_pk_add_f32 v[172:173], v[172:173], v[184:185]
	v_pk_add_f32 v[174:175], v[174:175], v[186:187]
	ds_bpermute_b32 v184, v84, v172
	ds_bpermute_b32 v185, v84, v173
	ds_bpermute_b32 v186, v84, v174
	ds_bpermute_b32 v187, v84, v175
	s_waitcnt lgkmcnt(0)
	v_pk_add_f32 v[172:173], v[172:173], v[184:185]
	v_pk_add_f32 v[174:175], v[174:175], v[186:187]
	ds_bpermute_b32 v184, v85, v172
	ds_bpermute_b32 v185, v85, v173
	ds_bpermute_b32 v186, v85, v174
	ds_bpermute_b32 v187, v85, v175
	s_waitcnt lgkmcnt(0)
	v_pk_add_f32 v[172:173], v[172:173], v[184:185]
	v_pk_add_f32 v[174:175], v[174:175], v[186:187]
	ds_bpermute_b32 v184, v86, v172
	ds_bpermute_b32 v185, v86, v173
	ds_bpermute_b32 v186, v86, v174
	ds_bpermute_b32 v187, v86, v175
	s_waitcnt lgkmcnt(0)
	v_pk_add_f32 v[172:173], v[172:173], v[184:185]
	v_pk_add_f32 v[174:175], v[174:175], v[186:187]
	ds_bpermute_b32 v184, v87, v172
	ds_bpermute_b32 v185, v87, v173
	ds_bpermute_b32 v186, v87, v174
	ds_bpermute_b32 v187, v87, v175
	s_waitcnt lgkmcnt(0)
	v_pk_add_f32 v[172:173], v[172:173], v[184:185]
	v_pk_add_f32 v[174:175], v[174:175], v[186:187]
	ds_bpermute_b32 v184, v88, v172
	ds_bpermute_b32 v185, v88, v173
	ds_bpermute_b32 v186, v88, v174
	ds_bpermute_b32 v187, v88, v175
	s_waitcnt lgkmcnt(0)
	v_pk_add_f32 v[172:173], v[172:173], v[184:185]
	v_pk_add_f32 v[174:175], v[174:175], v[186:187]
	v_fma_f32 v172, v172, s34, v178
	v_fma_f32 v173, v173, s34, v178
	v_fma_f32 v174, v174, s34, v178
	v_fma_f32 v175, v175, s34, v178
	v_mul_f32_e32 v184, 0x4b800000, v172
	v_mul_f32_e32 v185, 0x4b800000, v173
	v_mul_f32_e32 v186, 0x4b800000, v174
	v_mul_f32_e32 v187, 0x4b800000, v175
	s_waitcnt vmcnt(0)
	v_cmp_gt_f32_e64 s[50:51], s62, v172
	v_cmp_gt_f32_e64 s[52:53], s62, v173
	v_cmp_gt_f32_e64 s[30:31], s62, v174
	v_cmp_gt_f32_e32 vcc, s62, v175
	s_nop 1
	v_cndmask_b32_e64 v172, v172, v184, s[50:51]
	v_cndmask_b32_e64 v173, v173, v185, s[52:53]
	v_cndmask_b32_e64 v174, v174, v186, s[30:31]
	v_cndmask_b32_e32 v175, v175, v187, vcc
	v_rsq_f32_e32 v172, v172
	v_rsq_f32_e32 v173, v173
	v_rsq_f32_e32 v174, v174
	v_rsq_f32_e32 v175, v175
	s_nop 0
	v_mul_f32_e32 v184, 0x45800000, v172
	v_mul_f32_e32 v185, 0x45800000, v173
	v_mul_f32_e32 v186, 0x45800000, v174
	v_mul_f32_e32 v187, 0x45800000, v175
	v_cndmask_b32_e64 v188, v172, v184, s[50:51]
	v_cndmask_b32_e64 v190, v173, v185, s[52:53]
	v_cndmask_b32_e64 v192, v174, v186, s[30:31]
	v_cndmask_b32_e32 v194, v175, v187, vcc
	v_pk_add_f32 v[126:127], v[126:127], 1.0 op_sel_hi:[1,0]
	v_pk_add_f32 v[128:129], v[128:129], 1.0 op_sel_hi:[1,0]
	v_pk_add_f32 v[130:131], v[130:131], 1.0 op_sel_hi:[1,0]
	v_pk_add_f32 v[132:133], v[132:133], 1.0 op_sel_hi:[1,0]
	v_pk_add_f32 v[134:135], v[134:135], 1.0 op_sel_hi:[1,0]
	v_pk_add_f32 v[136:137], v[136:137], 1.0 op_sel_hi:[1,0]
	v_pk_add_f32 v[138:139], v[138:139], 1.0 op_sel_hi:[1,0]
	v_pk_add_f32 v[140:141], v[140:141], 1.0 op_sel_hi:[1,0]
	v_pk_mul_f32 v[0:1], v[0:1], v[188:189] op_sel_hi:[1,0]
	v_pk_mul_f32 v[2:3], v[2:3], v[188:189] op_sel_hi:[1,0]
	v_pk_mul_f32 v[0:1], v[156:157], v[0:1]
	v_pk_mul_f32 v[2:3], v[158:159], v[2:3]
	v_pk_fma_f32 v[0:1], v[126:127], v[0:1], v[110:111]
	v_pk_fma_f32 v[2:3], v[128:129], v[2:3], v[112:113]
	v_cvt_pk_bf16_f32 v0, v0, v1
	v_cvt_pk_bf16_f32 v1, v2, v3
	global_store_dwordx2 v[198:199], v[0:1], off offset:-3584
; DI unsigned pk2(float lo, float hi) { f32x2 v = {lo, hi}; bf16x2_t b = __builtin_convertvector(v, bf16x2_t); return __builtin_bit_cast(unsigned, b); }
; DI void normmod_phase(const float* xl, const float* xc, const float* g, const float* modl  , int cshift, int cscale, bf16_t* H, int nrows, int gw, int NGW, int lane,
;                       const float* part  , const float* pgate  , float* xc_out) {
;     ...
;     auto st = [&](const int row, const f32x4 (&v)[4], const float rs) __attribute__((always_inline)) {
;         const float* mp = modl + (size_t)((row < ML) ? (row >> 12) : 16) * 6144;
; #pragma unroll
;         for (int j = 0; j < 4; ++j) { const int c = lane * 4 + 256 * j;
;             const f32x4 gg = *(const f32x4*)(g + c), sh = *(const f32x4*)(mp + cshift * 1024 + c), scl = *(const f32x4*)(mp + cscale * 1024 + c);
;             const f32x4 y = (v[j] * rs) * gg * (scl + 1.f) + sh;
;             u32x2 o; o.x = pk2(y[0], y[1]); o.y = pk2(y[2], y[3]);
;             *(u32x2*)(H + (size_t)row * D + c) = o; } };
;     ...
;         float sA = ld(row, vA), sB = ld(row + 1, vB), sC = ld(row + 2, vC), sD = ld(row + 3, vD);
	v_pk_mul_f32 v[4:5], v[4:5], v[188:189] op_sel_hi:[1,0]
	v_pk_mul_f32 v[6:7], v[6:7], v[188:189] op_sel_hi:[1,0]
	v_pk_mul_f32 v[4:5], v[160:161], v[4:5]
	v_pk_mul_f32 v[6:7], v[162:163], v[6:7]
	v_pk_fma_f32 v[4:5], v[130:131], v[4:5], v[114:115]
	v_pk_fma_f32 v[6:7], v[132:133], v[6:7], v[116:117]
	v_cvt_pk_bf16_f32 v4, v4, v5
	v_cvt_pk_bf16_f32 v5, v6, v7
	global_store_dwordx2 v[198:199], v[4:5], off offset:-3072
	v_pk_mul_f32 v[8:9], v[8:9], v[188:189] op_sel_hi:[1,0]
	v_pk_mul_f32 v[10:11], v[10:11], v[188:189] op_sel_hi:[1,0]
	v_pk_mul_f32 v[8:9], v[164:165], v[8:9]
	v_pk_mul_f32 v[10:11], v[166:167], v[10:11]
	v_pk_fma_f32 v[8:9], v[134:135], v[8:9], v[118:119]
	v_pk_fma_f32 v[10:11], v[136:137], v[10:11], v[120:121]
	v_cvt_pk_bf16_f32 v8, v8, v9
	v_cvt_pk_bf16_f32 v9, v10, v11
	global_store_dwordx2 v[198:199], v[8:9], off offset:-2560
	v_pk_mul_f32 v[12:13], v[12:13], v[188:189] op_sel_hi:[1,0]
	v_pk_mul_f32 v[14:15], v[14:15], v[188:189] op_sel_hi:[1,0]
	v_pk_mul_f32 v[12:13], v[168:169], v[12:13]
	v_pk_mul_f32 v[14:15], v[170:171], v[14:15]
	v_pk_fma_f32 v[12:13], v[138:139], v[12:13], v[122:123]
	v_pk_fma_f32 v[14:15], v[140:141], v[14:15], v[124:125]
	v_cvt_pk_bf16_f32 v12, v12, v13
	v_cvt_pk_bf16_f32 v13, v14, v15
	global_store_dwordx2 v[198:199], v[12:13], off offset:-2048
	global_load_dwordx4 v[0:3], v76, s[42:43]
	global_load_dwordx4 v[4:7], v76, s[42:43] offset:1024
	global_load_dwordx4 v[8:11], v76, s[42:43] offset:2048
	global_load_dwordx4 v[12:15], v76, s[42:43] offset:3072
	v_pk_mul_f32 v[16:17], v[16:17], v[190:191] op_sel_hi:[1,0]
	v_pk_mul_f32 v[18:19], v[18:19], v[190:191] op_sel_hi:[1,0]
	v_pk_mul_f32 v[16:17], v[156:157], v[16:17]
	v_pk_mul_f32 v[18:19], v[158:159], v[18:19]
	v_pk_fma_f32 v[16:17], v[126:127], v[16:17], v[110:111]
	v_pk_fma_f32 v[18:19], v[128:129], v[18:19], v[112:113]
	v_cvt_pk_bf16_f32 v16, v16, v17
	v_cvt_pk_bf16_f32 v17, v18, v19
	global_store_dwordx2 v[198:199], v[16:17], off offset:-1536
	v_pk_mul_f32 v[20:21], v[20:21], v[190:191] op_sel_hi:[1,0]
	v_pk_mul_f32 v[22:23], v[22:23], v[190:191] op_sel_hi:[1,0]
	v_pk_mul_f32 v[20:21], v[160:161], v[20:21]
	v_pk_mul_f32 v[22:23], v[162:163], v[22:23]
	v_pk_fma_f32 v[20:21], v[130:131], v[20:21], v[114:115]
	v_pk_fma_f32 v[22:23], v[132:133], v[22:23], v[116:117]
	v_cvt_pk_bf16_f32 v20, v20, v21
	v_cvt_pk_bf16_f32 v21, v22, v23
	global_store_dwordx2 v[198:199], v[20:21], off offset:-1024
	v_pk_mul_f32 v[24:25], v[24:25], v[190:191] op_sel_hi:[1,0]
	v_pk_mul_f32 v[26:27], v[26:27], v[190:191] op_sel_hi:[1,0]
	v_pk_mul_f32 v[24:25], v[164:165], v[24:25]
	v_pk_mul_f32 v[26:27], v[166:167], v[26:27]
	v_pk_fma_f32 v[24:25], v[134:135], v[24:25], v[118:119]
	v_pk_fma_f32 v[26:27], v[136:137], v[26:27], v[120:121]
	v_cvt_pk_bf16_f32 v24, v24, v25
	v_cvt_pk_bf16_f32 v25, v26, v27
	global_store_dwordx2 v[198:199], v[24:25], off offset:-512
	v_pk_mul_f32 v[28:29], v[28:29], v[190:191] op_sel_hi:[1,0]
	v_pk_mul_f32 v[30:31], v[30:31], v[190:191] op_sel_hi:[1,0]
	v_pk_mul_f32 v[28:29], v[168:169], v[28:29]
	v_pk_mul_f32 v[30:31], v[170:171], v[30:31]
	v_pk_fma_f32 v[28:29], v[138:139], v[28:29], v[122:123]
	v_pk_fma_f32 v[30:31], v[140:141], v[30:31], v[124:125]
	v_cvt_pk_bf16_f32 v28, v28, v29
	v_cvt_pk_bf16_f32 v29, v30, v31
	global_store_dwordx2 v[78:79], v[28:29], off offset:-4096
	global_load_dwordx4 v[16:19], v76, s[4:5]
	global_load_dwordx4 v[20:23], v76, s[4:5] offset:1024
	global_load_dwordx4 v[24:27], v76, s[4:5] offset:2048
	global_load_dwordx4 v[28:31], v76, s[4:5] offset:3072
	v_pk_mul_f32 v[32:33], v[32:33], v[192:193] op_sel_hi:[1,0]
	v_pk_mul_f32 v[34:35], v[34:35], v[192:193] op_sel_hi:[1,0]
	v_pk_mul_f32 v[32:33], v[156:157], v[32:33]
	v_pk_mul_f32 v[34:35], v[158:159], v[34:35]
	v_pk_fma_f32 v[32:33], v[126:127], v[32:33], v[110:111]
	v_pk_fma_f32 v[34:35], v[128:129], v[34:35], v[112:113]
; DI unsigned pk2(float lo, float hi) { f32x2 v = {lo, hi}; bf16x2_t b = __builtin_convertvector(v, bf16x2_t); return __builtin_bit_cast(unsigned, b); }
; DI void normmod_phase(const float* xl, const float* xc, const float* g, const float* modl  , int cshift, int cscale, bf16_t* H, int nrows, int gw, int NGW, int lane,
;                       const float* part  , const float* pgate  , float* xc_out) {
;     ...
;     auto st = [&](const int row, const f32x4 (&v)[4], const float rs) __attribute__((always_inline)) {
;         const float* mp = modl + (size_t)((row < ML) ? (row >> 12) : 16) * 6144;
; #pragma unroll
;         for (int j = 0; j < 4; ++j) { const int c = lane * 4 + 256 * j;
;             const f32x4 gg = *(const f32x4*)(g + c), sh = *(const f32x4*)(mp + cshift * 1024 + c), scl = *(const f32x4*)(mp + cscale * 1024 + c);
;             const f32x4 y = (v[j] * rs) * gg * (scl + 1.f) + sh;
;             u32x2 o; o.x = pk2(y[0], y[1]); o.y = pk2(y[2], y[3]);
;             *(u32x2*)(H + (size_t)row * D + c) = o; } };
;     for (int row = gw * 4; row < (nrows < ML ? nrows : ML); row += NGW * 4) {
	v_cvt_pk_bf16_f32 v32, v32, v33
	v_cvt_pk_bf16_f32 v33, v34, v35
	global_store_dwordx2 v[78:79], v[32:33], off offset:-3584
	v_pk_mul_f32 v[36:37], v[36:37], v[192:193] op_sel_hi:[1,0]
	v_pk_mul_f32 v[38:39], v[38:39], v[192:193] op_sel_hi:[1,0]
	v_pk_mul_f32 v[36:37], v[160:161], v[36:37]
	v_pk_mul_f32 v[38:39], v[162:163], v[38:39]
	v_pk_fma_f32 v[36:37], v[130:131], v[36:37], v[114:115]
	v_pk_fma_f32 v[38:39], v[132:133], v[38:39], v[116:117]
	v_cvt_pk_bf16_f32 v36, v36, v37
	v_cvt_pk_bf16_f32 v37, v38, v39
	global_store_dwordx2 v[78:79], v[36:37], off offset:-3072
	v_pk_mul_f32 v[40:41], v[40:41], v[192:193] op_sel_hi:[1,0]
	v_pk_mul_f32 v[42:43], v[42:43], v[192:193] op_sel_hi:[1,0]
	v_pk_mul_f32 v[40:41], v[164:165], v[40:41]
	v_pk_mul_f32 v[42:43], v[166:167], v[42:43]
	v_pk_fma_f32 v[40:41], v[134:135], v[40:41], v[118:119]
	v_pk_fma_f32 v[42:43], v[136:137], v[42:43], v[120:121]
	v_cvt_pk_bf16_f32 v40, v40, v41
	v_cvt_pk_bf16_f32 v41, v42, v43
	global_store_dwordx2 v[78:79], v[40:41], off offset:-2560
	v_pk_mul_f32 v[44:45], v[44:45], v[192:193] op_sel_hi:[1,0]
	v_pk_mul_f32 v[46:47], v[46:47], v[192:193] op_sel_hi:[1,0]
	v_pk_mul_f32 v[44:45], v[168:169], v[44:45]
	v_pk_mul_f32 v[46:47], v[170:171], v[46:47]
	v_pk_fma_f32 v[44:45], v[138:139], v[44:45], v[122:123]
	v_pk_fma_f32 v[46:47], v[140:141], v[46:47], v[124:125]
	v_cvt_pk_bf16_f32 v44, v44, v45
	v_cvt_pk_bf16_f32 v45, v46, v47
	global_store_dwordx2 v[78:79], v[44:45], off offset:-2048
	global_load_dwordx4 v[32:35], v76, s[24:25]
	global_load_dwordx4 v[36:39], v76, s[24:25] offset:1024
	global_load_dwordx4 v[40:43], v76, s[24:25] offset:2048
	global_load_dwordx4 v[44:47], v76, s[24:25] offset:3072
	v_pk_mul_f32 v[48:49], v[48:49], v[194:195] op_sel_hi:[1,0]
	v_pk_mul_f32 v[50:51], v[50:51], v[194:195] op_sel_hi:[1,0]
	v_pk_mul_f32 v[48:49], v[156:157], v[48:49]
	v_pk_mul_f32 v[50:51], v[158:159], v[50:51]
	v_pk_fma_f32 v[48:49], v[126:127], v[48:49], v[110:111]
	v_pk_fma_f32 v[50:51], v[128:129], v[50:51], v[112:113]
	v_cvt_pk_bf16_f32 v48, v48, v49
	v_cvt_pk_bf16_f32 v49, v50, v51
	global_store_dwordx2 v[78:79], v[48:49], off offset:-1536
	v_pk_mul_f32 v[52:53], v[52:53], v[194:195] op_sel_hi:[1,0]
	v_pk_mul_f32 v[54:55], v[54:55], v[194:195] op_sel_hi:[1,0]
	v_pk_mul_f32 v[52:53], v[160:161], v[52:53]
	v_pk_mul_f32 v[54:55], v[162:163], v[54:55]
	v_pk_fma_f32 v[52:53], v[130:131], v[52:53], v[114:115]
	v_pk_fma_f32 v[54:55], v[132:133], v[54:55], v[116:117]
	v_cvt_pk_bf16_f32 v52, v52, v53
	v_cvt_pk_bf16_f32 v53, v54, v55
	global_store_dwordx2 v[78:79], v[52:53], off offset:-1024
	v_pk_mul_f32 v[56:57], v[56:57], v[194:195] op_sel_hi:[1,0]
	v_pk_mul_f32 v[58:59], v[58:59], v[194:195] op_sel_hi:[1,0]
	v_pk_mul_f32 v[56:57], v[164:165], v[56:57]
	v_pk_mul_f32 v[58:59], v[166:167], v[58:59]
	v_pk_fma_f32 v[56:57], v[134:135], v[56:57], v[118:119]
	v_pk_fma_f32 v[58:59], v[136:137], v[58:59], v[120:121]
	v_cvt_pk_bf16_f32 v56, v56, v57
	v_cvt_pk_bf16_f32 v57, v58, v59
	global_store_dwordx2 v[78:79], v[56:57], off offset:-512
	v_pk_mul_f32 v[60:61], v[60:61], v[194:195] op_sel_hi:[1,0]
	v_pk_mul_f32 v[62:63], v[62:63], v[194:195] op_sel_hi:[1,0]
	v_pk_mul_f32 v[60:61], v[168:169], v[60:61]
	v_pk_mul_f32 v[62:63], v[170:171], v[62:63]
	v_pk_fma_f32 v[60:61], v[138:139], v[60:61], v[122:123]
	v_pk_fma_f32 v[62:63], v[140:141], v[62:63], v[124:125]
	v_cvt_pk_bf16_f32 v60, v60, v61
	v_cvt_pk_bf16_f32 v61, v62, v63
	global_store_dwordx2 v[78:79], v[60:61], off
	global_load_dwordx4 v[48:51], v76, s[48:49]
	global_load_dwordx4 v[52:55], v76, s[48:49] offset:1024
	global_load_dwordx4 v[56:59], v76, s[48:49] offset:2048
	global_load_dwordx4 v[60:63], v76, s[48:49] offset:3072
	s_add_i32 s20, s20, s26
	v_lshl_add_u64 v[78:79], v[78:79], 0, s[46:47]
	s_add_i32 s4, s20, 0xffff
	s_cmp_gt_i32 s4, 0xffff
	s_cbranch_scc0 .LBB0_557
	s_waitcnt vmcnt(0)
